# P0 row-rmsnorm loop: 64-lane sum of squares reduced with DPP row ops plus v_readlane broadcasts instead of six ds_bpermute round trips
# speedup vs baseline: 1.0029x; 1.0029x over previous
; __device__ __forceinline__ void rms_row_to_bf16(const float* xrow, const float* g, bf16* orow, int lane) {
;     const f32x4* xr = (const f32x4*)xrow + lane; const f32x4* gr = (const f32x4*)g + lane;
;     f32x4 v[8]; float s = 0.f;
; #pragma unroll
;     for (int j = 0; j < 8; ++j) { v[j] = __builtin_nontemporal_load(xr + 64 * j); s += (v[j].x * v[j].x + v[j].y * v[j].y) + (v[j].z * v[j].z + v[j].w * v[j].w); }
;     const float rstd = rsqrtf(wave_sum(s) * (1.0f / 2048.0f) + 1e-6f);
; __global__ void __launch_bounds__(NWAVES * 64, 2) fwd(Params P) {
;     ...
;         for (int m = gw; m < NTOK; m += NGW) rms_row_to_bf16(x + (size_t)m * D, g_mix, UB + (size_t)m * D, lane);
.LBB0_68:
	global_load_dwordx4 v[46:49], v[34:35], off offset:-4096 nt
	global_load_dwordx4 v[50:53], v[34:35], off offset:-3072 nt
	global_load_dwordx4 v[20:23], v[34:35], off offset:-2048 nt
	global_load_dwordx4 v[12:15], v[34:35], off nt
	global_load_dwordx4 v[16:19], v[34:35], off offset:-1024 nt
	global_load_dwordx4 v[8:11], v[34:35], off offset:1024 nt
	global_load_dwordx4 v[0:3], v[34:35], off offset:3072 nt
	global_load_dwordx4 v[4:7], v[34:35], off offset:2048 nt
	s_add_i32 s4, s4, s16
	v_lshl_add_u64 v[34:35], v[34:35], 0, s[18:19]
	s_cmpk_gt_i32 s4, 0x3fff
	s_waitcnt vmcnt(7)
	v_mov_b32_e32 v60, v47
	s_waitcnt vmcnt(6)
	v_mov_b32_e32 v61, v51
	v_mov_b32_e32 v64, v49
	v_mov_b32_e32 v65, v53
	v_mov_b32_e32 v58, v46
	v_mov_b32_e32 v59, v50
	v_mov_b32_e32 v62, v48
	v_mov_b32_e32 v63, v52
	s_waitcnt vmcnt(5)
	v_pk_mul_f32 v[66:67], v[22:23], v[22:23]
	v_pk_mul_f32 v[68:69], v[20:21], v[20:21]
	v_pk_mul_f32 v[60:61], v[60:61], v[60:61]
	v_pk_mul_f32 v[64:65], v[64:65], v[64:65]
	v_pk_mov_b32 v[82:83], v[68:69], v[66:67] op_sel:[1,0]
	v_mov_b32_e32 v69, v67
	v_pk_fma_f32 v[58:59], v[58:59], v[58:59], v[60:61]
	v_pk_fma_f32 v[60:61], v[62:63], v[62:63], v[64:65]
	s_waitcnt vmcnt(3)
	v_mul_f32_e32 v70, v17, v17
	v_mul_f32_e32 v72, v19, v19
	v_pk_add_f32 v[62:63], v[82:83], v[68:69]
	v_pk_add_f32 v[58:59], v[58:59], v[60:61]
	v_mul_f32_e32 v45, v12, v12
	v_mul_f32_e32 v81, v13, v13
	v_mul_f32_e32 v84, v14, v14
	v_mul_f32_e32 v85, v15, v15
	v_pk_fma_f32 v[66:67], v[16:17], v[16:17], v[70:71] op_sel_hi:[1,1,0]
	v_pk_fma_f32 v[70:71], v[18:19], v[18:19], v[72:73] op_sel_hi:[1,1,0]
	v_pk_add_f32 v[60:61], v[62:63], v[62:63] op_sel:[0,1] op_sel_hi:[1,0]
	v_pk_add_f32 v[58:59], v[58:59], v[58:59] op_sel:[0,1] op_sel_hi:[1,0]
	s_waitcnt vmcnt(2)
	v_pk_mul_f32 v[74:75], v[10:11], v[10:11]
	v_pk_mul_f32 v[76:77], v[8:9], v[8:9]
	v_mov_b32_e32 v67, v84
	v_mov_b32_e32 v71, v85
	v_mov_b32_e32 v61, v81
	v_mov_b32_e32 v59, v45
	v_pk_mov_b32 v[72:73], v[76:77], v[74:75] op_sel:[1,0]
	v_mov_b32_e32 v77, v75
	v_pk_add_f32 v[62:63], v[66:67], v[70:71]
	v_pk_add_f32 v[58:59], v[58:59], v[60:61]
	s_waitcnt vmcnt(0)
; __device__ __forceinline__ unsigned pk2(float lo, float hi) { return f2bf(lo) | (f2bf(hi) << 16); }
; __device__ __forceinline__ float wave_sum(float v) {
; #pragma unroll
;     for (int o = 1; o < 64; o <<= 1) v += __shfl_xor(v, o);
;     return v;
; __device__ __forceinline__ void rms_row_to_bf16(const float* xrow, const float* g, bf16* orow, int lane) {
;     ...
;     const float rstd = rsqrtf(wave_sum(s) * (1.0f / 2048.0f) + 1e-6f);
;     unsigned long long* o8 = (unsigned long long*)orow + lane;
; #pragma unroll
;     for (int j = 0; j < 8; ++j) { const f32x4 gg = gr[64 * j];
;         o8[64 * j] = (unsigned long long)pk2(v[j].x * rstd * gg.x, v[j].y * rstd * gg.y) | ((unsigned long long)pk2(v[j].z * rstd * gg.z, v[j].w * rstd * gg.w) << 32); }
	v_mul_f32_e32 v78, v5, v5
	v_mul_f32_e32 v80, v7, v7
	v_pk_add_f32 v[64:65], v[72:73], v[76:77]
	v_pk_add_f32 v[58:59], v[58:59], v[62:63]
	v_mul_f32_e32 v86, v0, v0
	v_mul_f32_e32 v87, v1, v1
	v_mul_f32_e32 v88, v2, v2
	v_mul_f32_e32 v89, v3, v3
	v_pk_fma_f32 v[74:75], v[4:5], v[4:5], v[78:79] op_sel_hi:[1,1,0]
	v_pk_fma_f32 v[78:79], v[6:7], v[6:7], v[80:81] op_sel_hi:[1,1,0]
	v_pk_add_f32 v[64:65], v[64:65], v[64:65] op_sel:[0,1] op_sel_hi:[1,0]
	v_pk_add_f32 v[58:59], v[58:59], v[58:59] op_sel:[0,1] op_sel_hi:[1,0]
	v_mov_b32_e32 v75, v88
	v_mov_b32_e32 v79, v89
	v_mov_b32_e32 v65, v87
	v_mov_b32_e32 v59, v86
	v_pk_add_f32 v[66:67], v[74:75], v[78:79]
	v_pk_add_f32 v[58:59], v[58:59], v[64:65]
	s_nop 0
	v_pk_add_f32 v[58:59], v[58:59], v[66:67]
	s_nop 0
	v_add_f32_e32 v45, v58, v59
	s_nop 1
	v_add_f32_dpp v45, v45, v45 quad_perm:[1,0,3,2] row_mask:0xf bank_mask:0xf
	s_nop 1
	v_add_f32_dpp v45, v45, v45 quad_perm:[2,3,0,1] row_mask:0xf bank_mask:0xf
	s_nop 1
	v_add_f32_dpp v45, v45, v45 row_half_mirror row_mask:0xf bank_mask:0xf
	s_nop 1
	v_add_f32_dpp v45, v45, v45 row_mirror row_mask:0xf bank_mask:0xf
	s_nop 0
	v_readlane_b32 s98, v45, 0
	v_readlane_b32 s99, v45, 16
	v_readlane_b32 s100, v45, 32
	v_readlane_b32 s101, v45, 48
	s_nop 1
	v_mov_b32_e32 v45, s98
	v_add_f32_e32 v45, s99, v45
	v_add_f32_e32 v45, s100, v45
	v_add_f32_e32 v45, s101, v45
	v_fmamk_f32 v45, v45, 0x3a000000, v44
	v_mul_f32_e32 v58, 0x4b800000, v45
	v_cmp_gt_f32_e32 vcc, s0, v45
	s_nop 1
	v_cndmask_b32_e32 v45, v45, v58, vcc
	v_rsq_f32_e32 v45, v45
	s_nop 0
	v_mul_f32_e32 v58, 0x45800000, v45
	v_cndmask_b32_e32 v45, v45, v58, vcc
	v_mul_f32_e32 v46, v46, v45
	v_mul_f32_e32 v48, v48, v45
	v_mul_f32_e32 v47, v47, v45
	v_mul_f32_e32 v49, v49, v45
	v_mul_f32_e32 v46, v188, v46
	v_mul_f32_e32 v48, v190, v48
	v_mul_f32_e32 v47, v189, v47
	v_mul_f32_e32 v49, v191, v49
	v_bfe_u32 v54, v46, 16, 1
	v_bfe_u32 v56, v48, 16, 1
	v_bfe_u32 v55, v47, 16, 1
	v_bfe_u32 v57, v49, 16, 1
	v_add3_u32 v46, v46, v54, s1
	v_add3_u32 v48, v48, v56, s1
	v_add3_u32 v47, v47, v55, s1
	v_add3_u32 v49, v49, v57, s1
	v_lshrrev_b32_e32 v46, 16, v46
	v_lshrrev_b32_e32 v48, 16, v48
	v_and_or_b32 v46, v47, s5, v46
	v_and_or_b32 v47, v49, s5, v48
	global_store_dwordx2 v[36:37], v[46:47], off
	v_mul_f32_e32 v50, v50, v45
	v_mul_f32_e32 v52, v52, v45
	v_mul_f32_e32 v51, v51, v45
	v_mul_f32_e32 v53, v53, v45
	v_mul_f32_e32 v20, v20, v45
	v_mul_f32_e32 v22, v22, v45
	v_mul_f32_e32 v21, v21, v45
	v_mul_f32_e32 v23, v23, v45
	v_mul_f32_e32 v16, v16, v45
	v_mul_f32_e32 v18, v18, v45
	v_mul_f32_e32 v17, v17, v45
	v_mul_f32_e32 v19, v19, v45
	v_mul_f32_e32 v12, v12, v45
	v_mul_f32_e32 v14, v14, v45
	v_mul_f32_e32 v13, v13, v45
	v_mul_f32_e32 v15, v15, v45
	v_mul_f32_e32 v8, v8, v45
	v_mul_f32_e32 v10, v10, v45
	v_mul_f32_e32 v9, v9, v45
	v_mul_f32_e32 v11, v11, v45
	v_mul_f32_e32 v4, v4, v45
	v_mul_f32_e32 v6, v6, v45
	v_mul_f32_e32 v5, v5, v45
	v_mul_f32_e32 v7, v7, v45
	v_mul_f32_e32 v0, v0, v45
	v_mul_f32_e32 v2, v2, v45
	v_mul_f32_e32 v1, v1, v45
	v_mul_f32_e32 v3, v3, v45
	v_mul_f32_e32 v220, v192, v50
	v_mul_f32_e32 v222, v194, v52
	v_mul_f32_e32 v221, v193, v51
	v_mul_f32_e32 v223, v195, v53
	v_bfe_u32 v50, v220, 16, 1
	v_bfe_u32 v52, v222, 16, 1
	v_bfe_u32 v51, v221, 16, 1
	v_bfe_u32 v53, v223, 16, 1
	v_add3_u32 v220, v220, v50, s1
	v_add3_u32 v222, v222, v52, s1
	v_add3_u32 v221, v221, v51, s1
	v_add3_u32 v223, v223, v53, s1
	v_lshrrev_b32_e32 v220, 16, v220
	v_lshrrev_b32_e32 v222, 16, v222
	v_and_or_b32 v220, v221, s5, v220
	v_and_or_b32 v221, v223, s5, v222
	global_store_dwordx2 v[36:37], v[220:221], off offset:512
	v_mul_f32_e32 v20, v196, v20
	v_mul_f32_e32 v22, v198, v22
	v_mul_f32_e32 v21, v197, v21
	v_mul_f32_e32 v23, v199, v23
	v_bfe_u32 v46, v20, 16, 1
	v_bfe_u32 v48, v22, 16, 1
	v_bfe_u32 v47, v21, 16, 1
	v_bfe_u32 v49, v23, 16, 1
	v_add3_u32 v20, v20, v46, s1
	v_add3_u32 v22, v22, v48, s1
	v_add3_u32 v21, v21, v47, s1
	v_add3_u32 v23, v23, v49, s1
	v_lshrrev_b32_e32 v20, 16, v20
	v_lshrrev_b32_e32 v22, 16, v22
	v_and_or_b32 v20, v21, s5, v20
	v_and_or_b32 v21, v23, s5, v22
	global_store_dwordx2 v[36:37], v[20:21], off offset:1024
	v_mul_f32_e32 v16, v200, v16
	v_mul_f32_e32 v18, v202, v18
	v_mul_f32_e32 v17, v201, v17
	v_mul_f32_e32 v19, v203, v19
	v_bfe_u32 v20, v16, 16, 1
	v_bfe_u32 v22, v18, 16, 1
	v_bfe_u32 v21, v17, 16, 1
	v_bfe_u32 v23, v19, 16, 1
	v_add3_u32 v16, v16, v20, s1
	v_add3_u32 v18, v18, v22, s1
	v_add3_u32 v17, v17, v21, s1
	v_add3_u32 v19, v19, v23, s1
	v_lshrrev_b32_e32 v16, 16, v16
	v_lshrrev_b32_e32 v18, 16, v18
	v_and_or_b32 v16, v17, s5, v16
	v_and_or_b32 v17, v19, s5, v18
	global_store_dwordx2 v[36:37], v[16:17], off offset:1536
	v_mul_f32_e32 v12, v204, v12
	v_mul_f32_e32 v14, v206, v14
	v_mul_f32_e32 v13, v205, v13
	v_mul_f32_e32 v15, v207, v15
	v_bfe_u32 v16, v12, 16, 1
	v_bfe_u32 v18, v14, 16, 1
	v_bfe_u32 v17, v13, 16, 1
	v_bfe_u32 v19, v15, 16, 1
	v_add3_u32 v12, v12, v16, s1
	v_add3_u32 v14, v14, v18, s1
	v_add3_u32 v13, v13, v17, s1
	v_add3_u32 v15, v15, v19, s1
	v_lshrrev_b32_e32 v12, 16, v12
	v_lshrrev_b32_e32 v14, 16, v14
	v_and_or_b32 v12, v13, s5, v12
	v_and_or_b32 v13, v15, s5, v14
	global_store_dwordx2 v[36:37], v[12:13], off offset:2048
	v_mul_f32_e32 v8, v8, v208
	v_mul_f32_e32 v10, v10, v210
	v_mul_f32_e32 v9, v9, v209
	v_mul_f32_e32 v11, v11, v211
	v_bfe_u32 v12, v8, 16, 1
	v_bfe_u32 v14, v10, 16, 1
	v_bfe_u32 v13, v9, 16, 1
	v_bfe_u32 v15, v11, 16, 1
	v_add3_u32 v8, v8, v12, s1
	v_add3_u32 v10, v10, v14, s1
	v_add3_u32 v9, v9, v13, s1
	v_add3_u32 v11, v11, v15, s1
	v_lshrrev_b32_e32 v8, 16, v8
	v_lshrrev_b32_e32 v10, 16, v10
	v_and_or_b32 v8, v9, s5, v8
	v_and_or_b32 v9, v11, s5, v10
	global_store_dwordx2 v[36:37], v[8:9], off offset:2560
	v_mul_f32_e32 v4, v4, v212
	v_mul_f32_e32 v6, v6, v214
	v_mul_f32_e32 v5, v5, v213
	v_mul_f32_e32 v7, v7, v215
	v_bfe_u32 v8, v4, 16, 1
	v_bfe_u32 v10, v6, 16, 1
	v_bfe_u32 v9, v5, 16, 1
	v_bfe_u32 v11, v7, 16, 1
	v_add3_u32 v4, v4, v8, s1
	v_add3_u32 v6, v6, v10, s1
	v_add3_u32 v5, v5, v9, s1
	v_add3_u32 v7, v7, v11, s1
	v_lshrrev_b32_e32 v4, 16, v4
	v_lshrrev_b32_e32 v6, 16, v6
	v_and_or_b32 v4, v5, s5, v4
	v_and_or_b32 v5, v7, s5, v6
	global_store_dwordx2 v[36:37], v[4:5], off offset:3072
	v_mul_f32_e32 v0, v0, v216
	v_mul_f32_e32 v2, v2, v218
	v_mul_f32_e32 v1, v1, v217
	v_mul_f32_e32 v3, v3, v219
	v_bfe_u32 v4, v0, 16, 1
	v_bfe_u32 v6, v2, 16, 1
	v_bfe_u32 v5, v1, 16, 1
	v_bfe_u32 v7, v3, 16, 1
	v_add3_u32 v0, v0, v4, s1
	v_add3_u32 v2, v2, v6, s1
	v_add3_u32 v1, v1, v5, s1
	v_add3_u32 v3, v3, v7, s1
	v_lshrrev_b32_e32 v0, 16, v0
	v_lshrrev_b32_e32 v2, 16, v2
	v_and_or_b32 v0, v1, s5, v0
	v_and_or_b32 v1, v3, s5, v2
	global_store_dwordx2 v[36:37], v[0:1], off offset:3584
	v_lshl_add_u64 v[36:37], v[36:37], 0, s[20:21]
	s_cbranch_scc0 .LBB0_68
